# residual-GEMM epilogue (layers 1-3): the 16 serialised xb row loads of a unit issued up front into dead K-loop operand registers (12 + 4), counted vmcnt waits instead of full drains
# speedup vs baseline: 1.0022x; 1.0022x over previous
.LBB0_3620:
	v_add_u32_e32 v140, s26, v142
	v_lshlrev_b32_e32 v202, 12, v140
	v_lshl_add_u32 v202, v138, 1, v202
	global_load_dwordx4 v[170:173], v202, s[38:39]
	global_load_dwordx4 v[174:177], v202, s[38:39] offset:256
	s_add_u32 s98, s38, 0x10000
	s_addc_u32 s99, s39, 0
	global_load_dwordx4 v[178:181], v202, s[98:99]
	global_load_dwordx4 v[182:185], v202, s[98:99] offset:256
	s_add_u32 s98, s38, 0x20000
	s_addc_u32 s99, s39, 0
	global_load_dwordx4 v[186:189], v202, s[98:99]
	global_load_dwordx4 v[190:193], v202, s[98:99] offset:256
	s_add_u32 s98, s38, 0x30000
	s_addc_u32 s99, s39, 0
	global_load_dwordx4 v[194:197], v202, s[98:99]
	global_load_dwordx4 v[198:201], v202, s[98:99] offset:256
	s_add_u32 s98, s38, 0x80000
	s_addc_u32 s99, s39, 0
	global_load_dwordx4 v[206:209], v202, s[98:99]
	global_load_dwordx4 v[210:213], v202, s[98:99] offset:256
	s_add_u32 s98, s38, 0x90000
	s_addc_u32 s99, s39, 0
	global_load_dwordx4 v[214:217], v202, s[98:99]
	global_load_dwordx4 v[218:221], v202, s[98:99] offset:256
	v_ashrrev_i32_e32 v141, 31, v140
	v_lshlrev_b64 v[156:157], 12, v[140:141]
	v_lshl_add_u64 v[156:157], s[38:39], 0, v[156:157]
	v_lshl_add_u64 v[160:161], v[138:139], 1, v[156:157]
	s_waitcnt vmcnt(11)
	v_mov_b64 v[156:157], v[170:171]
	v_mov_b64 v[158:159], v[172:173]
	v_lshlrev_b32_e32 v162, 16, v156
	v_and_b32_e32 v163, 0xffff0000, v156
	v_lshlrev_b32_e32 v156, 16, v157
	v_and_b32_e32 v157, 0xffff0000, v157
	v_lshlrev_b32_e32 v168, 16, v158
	v_and_b32_e32 v169, 0xffff0000, v158
	v_lshlrev_b32_e32 v158, 16, v159
	v_and_b32_e32 v159, 0xffff0000, v159
	v_pk_add_f32 v[126:127], v[126:127], v[156:157]
	v_pk_add_f32 v[124:125], v[124:125], v[162:163]
	v_pk_add_f32 v[156:157], v[122:123], v[158:159]
	v_pk_add_f32 v[158:159], v[120:121], v[168:169]
	v_cvt_pk_bf16_f32 v120, v124, v125
	v_cvt_pk_bf16_f32 v121, v126, v127
	s_nop 0
	v_cvt_pk_bf16_f32 v122, v158, v159
	v_cvt_pk_bf16_f32 v123, v156, v157
	global_store_dwordx4 v[160:161], v[120:123], off
	s_nop 1
	v_mul_f32_e32 v120, v125, v125
	v_mul_f32_e32 v121, v127, v127
	v_fmac_f32_e32 v120, v124, v124
	v_fmac_f32_e32 v121, v126, v126
	v_add_f32_e32 v120, v120, v121
	v_mul_f32_e32 v121, v159, v159
	v_fmac_f32_e32 v121, v158, v158
	v_add_f32_e32 v120, v121, v120
	v_mul_f32_e32 v121, v157, v157
	v_fmac_f32_e32 v121, v156, v156
	v_add_f32_e32 v155, v121, v120
	s_waitcnt vmcnt(11)
	v_mov_b64 v[120:121], v[174:175]
	v_mov_b64 v[122:123], v[176:177]
	s_add_u32 s98, s38, 0xa0000
	s_addc_u32 s99, s39, 0
	global_load_dwordx4 v[170:173], v202, s[98:99]
	global_load_dwordx4 v[174:177], v202, s[98:99] offset:256
	v_lshlrev_b32_e32 v124, 16, v120
	v_and_b32_e32 v125, 0xffff0000, v120
	v_lshlrev_b32_e32 v120, 16, v121
	v_and_b32_e32 v121, 0xffff0000, v121
	v_lshlrev_b32_e32 v126, 16, v122
	v_and_b32_e32 v127, 0xffff0000, v122
	v_lshlrev_b32_e32 v122, 16, v123
	v_and_b32_e32 v123, 0xffff0000, v123
	v_pk_add_f32 v[118:119], v[118:119], v[120:121]
	v_pk_add_f32 v[116:117], v[116:117], v[124:125]
	v_pk_add_f32 v[120:121], v[114:115], v[122:123]
	v_pk_add_f32 v[122:123], v[112:113], v[126:127]
	v_cvt_pk_bf16_f32 v112, v116, v117
	v_cvt_pk_bf16_f32 v113, v118, v119
	s_nop 0
	v_cvt_pk_bf16_f32 v114, v122, v123
	v_cvt_pk_bf16_f32 v115, v120, v121
	global_store_dwordx4 v[160:161], v[112:115], off offset:256
	s_nop 1
	v_mul_f32_e32 v112, v117, v117
	v_mul_f32_e32 v113, v119, v119
	v_fmac_f32_e32 v112, v116, v116
	v_fmac_f32_e32 v113, v118, v118
	v_add_f32_e32 v112, v112, v113
	v_mul_f32_e32 v113, v123, v123
	v_fmac_f32_e32 v113, v122, v122
	v_add_f32_e32 v112, v113, v112
	v_mul_f32_e32 v113, v121, v121
	v_fmac_f32_e32 v113, v120, v120
	v_and_b32_e32 v114, 64, v204
	v_add_f32_e32 v112, v113, v112
	v_xor_b32_e32 v113, 16, v204
	v_add_u32_e32 v115, 64, v114
	v_cmp_lt_i32_e32 vcc, v113, v115
	v_add_f32_e32 v112, v155, v112
	s_nop 0
	v_cndmask_b32_e32 v113, v204, v113, vcc
	v_lshlrev_b32_e32 v114, 2, v113
	ds_bpermute_b32 v113, v114, v112
	s_waitcnt lgkmcnt(0)
	v_add_f32_e32 v112, v112, v113
	v_xor_b32_e32 v113, 32, v204
	v_cmp_lt_i32_e32 vcc, v113, v115
	s_nop 1
	v_cndmask_b32_e32 v113, v204, v113, vcc
	v_lshlrev_b32_e32 v115, 2, v113
	ds_bpermute_b32 v113, v115, v112
	s_and_saveexec_b64 s[0:1], s[34:35]
	s_cbranch_execz .LBB0_3622
	s_waitcnt lgkmcnt(0)
	v_add_f32_e32 v116, v112, v113
	s_lshl_b32 s22, s9, 2
	v_lshlrev_b64 v[112:113], 7, v[140:141]
	s_ashr_i32 s23, s22, 31
	v_lshl_add_u64 v[112:113], s[44:45], 0, v[112:113]
	v_lshl_add_u64 v[112:113], s[22:23], 2, v[112:113]
	s_lshl_b32 s40, s60, 2
	v_lshl_add_u64 v[112:113], v[112:113], 0, s[40:41]
	global_store_dword v[112:113], v116, off
.LBB0_3622:
	s_or_b64 exec, exec, s[0:1]
	v_or_b32_e32 v112, 16, v140
	s_waitcnt lgkmcnt(0)
	v_ashrrev_i32_e32 v113, 31, v112
	v_lshlrev_b64 v[116:117], 12, v[112:113]
	v_lshl_add_u64 v[116:117], s[38:39], 0, v[116:117]
	v_lshl_add_u64 v[120:121], v[138:139], 1, v[116:117]
	s_waitcnt vmcnt(13)
	v_mov_b64 v[116:117], v[178:179]
	v_mov_b64 v[118:119], v[180:181]
	v_lshlrev_b32_e32 v122, 16, v116
	v_and_b32_e32 v123, 0xffff0000, v116
	v_lshlrev_b32_e32 v116, 16, v117
	v_and_b32_e32 v117, 0xffff0000, v117
	v_lshlrev_b32_e32 v124, 16, v118
	v_and_b32_e32 v125, 0xffff0000, v118
	v_lshlrev_b32_e32 v118, 16, v119
	v_and_b32_e32 v119, 0xffff0000, v119
	v_pk_add_f32 v[116:117], v[110:111], v[116:117]
	v_pk_add_f32 v[122:123], v[108:109], v[122:123]
	v_pk_add_f32 v[118:119], v[106:107], v[118:119]
	v_pk_add_f32 v[124:125], v[104:105], v[124:125]
	v_cvt_pk_bf16_f32 v104, v122, v123
	v_cvt_pk_bf16_f32 v105, v116, v117
	v_mul_f32_e32 v123, v123, v123
	v_cvt_pk_bf16_f32 v106, v124, v125
	v_cvt_pk_bf16_f32 v107, v118, v119
	v_mul_f32_e32 v117, v117, v117
	v_mul_f32_e32 v125, v125, v125
	v_fmac_f32_e32 v123, v122, v122
	v_fmac_f32_e32 v117, v116, v116
	v_mul_f32_e32 v119, v119, v119
	v_fmac_f32_e32 v125, v124, v124
	v_add_f32_e32 v116, v123, v117
	v_fmac_f32_e32 v119, v118, v118
	v_add_f32_e32 v116, v125, v116
	v_add_f32_e32 v122, v119, v116
	global_store_dwordx4 v[120:121], v[104:107], off
	s_waitcnt vmcnt(13)
	v_mov_b64 v[108:109], v[182:183]
	v_mov_b64 v[110:111], v[184:185]
	s_add_u32 s98, s38, 0xb0000
	s_addc_u32 s99, s39, 0
	global_load_dwordx4 v[178:181], v202, s[98:99]
	global_load_dwordx4 v[182:185], v202, s[98:99] offset:256
	v_lshlrev_b32_e32 v116, 16, v108
	v_and_b32_e32 v117, 0xffff0000, v108
	v_lshlrev_b32_e32 v108, 16, v109
	v_and_b32_e32 v109, 0xffff0000, v109
	v_lshlrev_b32_e32 v118, 16, v110
	v_and_b32_e32 v119, 0xffff0000, v110
	v_lshlrev_b32_e32 v110, 16, v111
	v_and_b32_e32 v111, 0xffff0000, v111
	v_pk_add_f32 v[102:103], v[102:103], v[108:109]
	v_pk_add_f32 v[100:101], v[100:101], v[116:117]
	v_pk_add_f32 v[108:109], v[98:99], v[110:111]
	v_pk_add_f32 v[110:111], v[96:97], v[118:119]
	v_mul_f32_e32 v96, v101, v101
	v_mul_f32_e32 v97, v103, v103
	v_mul_f32_e32 v98, v111, v111
	v_fmac_f32_e32 v96, v100, v100
	v_fmac_f32_e32 v97, v102, v102
	v_mul_f32_e32 v99, v109, v109
	v_fmac_f32_e32 v98, v110, v110
	v_add_f32_e32 v96, v96, v97
	v_add_f32_e32 v96, v98, v96
	v_fmac_f32_e32 v99, v108, v108
	v_add_f32_e32 v96, v99, v96
	v_add_f32_e32 v96, v122, v96
	ds_bpermute_b32 v97, v114, v96
	v_cvt_pk_bf16_f32 v98, v100, v101
	v_cvt_pk_bf16_f32 v99, v102, v103
	v_cvt_pk_bf16_f32 v100, v110, v111
	v_cvt_pk_bf16_f32 v101, v108, v109
	s_waitcnt lgkmcnt(0)
	v_add_f32_e32 v96, v96, v97
	ds_bpermute_b32 v97, v115, v96
	global_store_dwordx4 v[120:121], v[98:101], off offset:256
	s_and_saveexec_b64 s[0:1], s[34:35]
	s_cbranch_execz .LBB0_3624
	s_waitcnt lgkmcnt(0)
	v_add_f32_e32 v98, v96, v97
	s_lshl_b32 s22, s9, 2
	v_lshlrev_b64 v[96:97], 7, v[112:113]
	s_ashr_i32 s23, s22, 31
	v_lshl_add_u64 v[96:97], s[44:45], 0, v[96:97]
	v_lshl_add_u64 v[96:97], s[22:23], 2, v[96:97]
	s_lshl_b32 s40, s60, 2
	v_lshl_add_u64 v[96:97], v[96:97], 0, s[40:41]
	global_store_dword v[96:97], v98, off
.LBB0_3624:
	s_or_b64 exec, exec, s[0:1]
	v_or_b32_e32 v96, 32, v140
	s_waitcnt lgkmcnt(0)
	v_ashrrev_i32_e32 v97, 31, v96
	v_lshlrev_b64 v[98:99], 12, v[96:97]
	v_lshl_add_u64 v[98:99], s[38:39], 0, v[98:99]
	v_lshl_add_u64 v[102:103], v[138:139], 1, v[98:99]
	s_waitcnt vmcnt(15)
	v_mov_b64 v[98:99], v[186:187]
	v_mov_b64 v[100:101], v[188:189]
	v_lshlrev_b32_e32 v104, 16, v98
	v_and_b32_e32 v105, 0xffff0000, v98
	v_lshlrev_b32_e32 v98, 16, v99
	v_and_b32_e32 v99, 0xffff0000, v99
	v_lshlrev_b32_e32 v106, 16, v100
	v_and_b32_e32 v107, 0xffff0000, v100
	v_lshlrev_b32_e32 v100, 16, v101
	v_and_b32_e32 v101, 0xffff0000, v101
	v_pk_add_f32 v[98:99], v[94:95], v[98:99]
	v_pk_add_f32 v[104:105], v[92:93], v[104:105]
	v_pk_add_f32 v[100:101], v[90:91], v[100:101]
	v_pk_add_f32 v[106:107], v[88:89], v[106:107]
	v_cvt_pk_bf16_f32 v88, v104, v105
	v_cvt_pk_bf16_f32 v89, v98, v99
	v_mul_f32_e32 v105, v105, v105
	v_cvt_pk_bf16_f32 v90, v106, v107
	v_cvt_pk_bf16_f32 v91, v100, v101
	v_mul_f32_e32 v99, v99, v99
	v_mul_f32_e32 v107, v107, v107
	v_fmac_f32_e32 v105, v104, v104
	v_fmac_f32_e32 v99, v98, v98
	v_mul_f32_e32 v101, v101, v101
	v_fmac_f32_e32 v107, v106, v106
	v_add_f32_e32 v98, v105, v99
	v_fmac_f32_e32 v101, v100, v100
	v_add_f32_e32 v98, v107, v98
	v_add_f32_e32 v104, v101, v98
	global_store_dwordx4 v[102:103], v[88:91], off
	s_waitcnt vmcnt(15)
	v_mov_b64 v[92:93], v[190:191]
	v_mov_b64 v[94:95], v[192:193]
	v_lshlrev_b32_e32 v98, 16, v92
	v_and_b32_e32 v99, 0xffff0000, v92
	v_lshlrev_b32_e32 v92, 16, v93
	v_and_b32_e32 v93, 0xffff0000, v93
	v_lshlrev_b32_e32 v100, 16, v94
	v_and_b32_e32 v101, 0xffff0000, v94
	v_lshlrev_b32_e32 v94, 16, v95
	v_and_b32_e32 v95, 0xffff0000, v95
	v_pk_add_f32 v[86:87], v[86:87], v[92:93]
	v_pk_add_f32 v[84:85], v[84:85], v[98:99]
	v_pk_add_f32 v[92:93], v[82:83], v[94:95]
	v_pk_add_f32 v[94:95], v[80:81], v[100:101]
	v_mul_f32_e32 v80, v85, v85
	v_mul_f32_e32 v81, v87, v87
	v_mul_f32_e32 v82, v95, v95
	v_fmac_f32_e32 v80, v84, v84
	v_fmac_f32_e32 v81, v86, v86
	v_mul_f32_e32 v83, v93, v93
	v_fmac_f32_e32 v82, v94, v94
	v_add_f32_e32 v80, v80, v81
	v_add_f32_e32 v80, v82, v80
	v_fmac_f32_e32 v83, v92, v92
	v_add_f32_e32 v80, v83, v80
	v_add_f32_e32 v80, v104, v80
	ds_bpermute_b32 v81, v114, v80
	v_cvt_pk_bf16_f32 v82, v84, v85
	v_cvt_pk_bf16_f32 v83, v86, v87
	v_cvt_pk_bf16_f32 v84, v94, v95
	v_cvt_pk_bf16_f32 v85, v92, v93
	s_waitcnt lgkmcnt(0)
	v_add_f32_e32 v80, v80, v81
	ds_bpermute_b32 v81, v115, v80
	global_store_dwordx4 v[102:103], v[82:85], off offset:256
	s_and_saveexec_b64 s[0:1], s[34:35]
	s_cbranch_execz .LBB0_3626
	s_waitcnt lgkmcnt(0)
	v_add_f32_e32 v82, v80, v81
	s_lshl_b32 s22, s9, 2
	v_lshlrev_b64 v[80:81], 7, v[96:97]
	s_ashr_i32 s23, s22, 31
	v_lshl_add_u64 v[80:81], s[44:45], 0, v[80:81]
	v_lshl_add_u64 v[80:81], s[22:23], 2, v[80:81]
	s_lshl_b32 s40, s60, 2
	v_lshl_add_u64 v[80:81], v[80:81], 0, s[40:41]
	global_store_dword v[80:81], v82, off
.LBB0_3626:
	s_or_b64 exec, exec, s[0:1]
	v_or_b32_e32 v80, 48, v140
	s_waitcnt lgkmcnt(0)
	v_ashrrev_i32_e32 v81, 31, v80
	v_lshlrev_b64 v[82:83], 12, v[80:81]
	v_lshl_add_u64 v[82:83], s[38:39], 0, v[82:83]
	v_lshl_add_u64 v[86:87], v[138:139], 1, v[82:83]
	s_waitcnt vmcnt(15)
	v_mov_b64 v[82:83], v[194:195]
	v_mov_b64 v[84:85], v[196:197]
	v_lshlrev_b32_e32 v88, 16, v82
	v_and_b32_e32 v89, 0xffff0000, v82
	v_lshlrev_b32_e32 v82, 16, v83
	v_and_b32_e32 v83, 0xffff0000, v83
	v_lshlrev_b32_e32 v90, 16, v84
	v_and_b32_e32 v91, 0xffff0000, v84
	v_lshlrev_b32_e32 v84, 16, v85
	v_and_b32_e32 v85, 0xffff0000, v85
	v_pk_add_f32 v[82:83], v[78:79], v[82:83]
	v_pk_add_f32 v[88:89], v[76:77], v[88:89]
	v_pk_add_f32 v[84:85], v[74:75], v[84:85]
	v_pk_add_f32 v[90:91], v[72:73], v[90:91]
	v_cvt_pk_bf16_f32 v72, v88, v89
	v_cvt_pk_bf16_f32 v73, v82, v83
	v_mul_f32_e32 v89, v89, v89
	v_cvt_pk_bf16_f32 v74, v90, v91
	v_cvt_pk_bf16_f32 v75, v84, v85
	v_mul_f32_e32 v83, v83, v83
	v_mul_f32_e32 v91, v91, v91
	v_fmac_f32_e32 v89, v88, v88
	v_fmac_f32_e32 v83, v82, v82
	v_mul_f32_e32 v85, v85, v85
	v_fmac_f32_e32 v91, v90, v90
	v_add_f32_e32 v82, v89, v83
	v_fmac_f32_e32 v85, v84, v84
	v_add_f32_e32 v82, v91, v82
	v_add_f32_e32 v88, v85, v82
	global_store_dwordx4 v[86:87], v[72:75], off
	s_waitcnt vmcnt(15)
	v_mov_b64 v[76:77], v[198:199]
	v_mov_b64 v[78:79], v[200:201]
	v_lshlrev_b32_e32 v82, 16, v76
	v_and_b32_e32 v83, 0xffff0000, v76
	v_lshlrev_b32_e32 v76, 16, v77
	v_and_b32_e32 v77, 0xffff0000, v77
	v_lshlrev_b32_e32 v84, 16, v78
	v_and_b32_e32 v85, 0xffff0000, v78
	v_lshlrev_b32_e32 v78, 16, v79
	v_and_b32_e32 v79, 0xffff0000, v79
	v_pk_add_f32 v[70:71], v[70:71], v[76:77]
	v_pk_add_f32 v[68:69], v[68:69], v[82:83]
	v_pk_add_f32 v[76:77], v[66:67], v[78:79]
	v_pk_add_f32 v[78:79], v[64:65], v[84:85]
	v_mul_f32_e32 v64, v69, v69
	v_mul_f32_e32 v65, v71, v71
	v_mul_f32_e32 v66, v79, v79
	v_fmac_f32_e32 v64, v68, v68
	v_fmac_f32_e32 v65, v70, v70
	v_mul_f32_e32 v67, v77, v77
	v_fmac_f32_e32 v66, v78, v78
	v_add_f32_e32 v64, v64, v65
	v_add_f32_e32 v64, v66, v64
	v_fmac_f32_e32 v67, v76, v76
	v_add_f32_e32 v64, v67, v64
	v_add_f32_e32 v64, v88, v64
	ds_bpermute_b32 v65, v114, v64
	v_cvt_pk_bf16_f32 v66, v68, v69
	v_cvt_pk_bf16_f32 v67, v70, v71
	v_cvt_pk_bf16_f32 v68, v78, v79
	v_cvt_pk_bf16_f32 v69, v76, v77
	s_waitcnt lgkmcnt(0)
	v_add_f32_e32 v64, v64, v65
	ds_bpermute_b32 v65, v115, v64
	global_store_dwordx4 v[86:87], v[66:69], off offset:256
	s_and_saveexec_b64 s[0:1], s[34:35]
	s_cbranch_execz .LBB0_3628
	s_waitcnt lgkmcnt(0)
	v_add_f32_e32 v66, v64, v65
	s_lshl_b32 s22, s9, 2
	v_lshlrev_b64 v[64:65], 7, v[80:81]
	s_ashr_i32 s23, s22, 31
	v_lshl_add_u64 v[64:65], s[44:45], 0, v[64:65]
	v_lshl_add_u64 v[64:65], s[22:23], 2, v[64:65]
	s_lshl_b32 s40, s60, 2
	v_lshl_add_u64 v[64:65], v[64:65], 0, s[40:41]
	global_store_dword v[64:65], v66, off
.LBB0_3628:
	s_or_b64 exec, exec, s[0:1]
	v_add_u32_e32 v64, 0x80, v140
	s_waitcnt lgkmcnt(0)
	v_ashrrev_i32_e32 v65, 31, v64
	v_lshlrev_b64 v[66:67], 12, v[64:65]
	v_lshl_add_u64 v[66:67], s[38:39], 0, v[66:67]
	v_lshl_add_u64 v[70:71], v[138:139], 1, v[66:67]
	s_waitcnt vmcnt(15)
	v_mov_b64 v[66:67], v[206:207]
	v_mov_b64 v[68:69], v[208:209]
	v_lshlrev_b32_e32 v72, 16, v66
	v_and_b32_e32 v73, 0xffff0000, v66
	v_lshlrev_b32_e32 v66, 16, v67
	v_and_b32_e32 v67, 0xffff0000, v67
	v_lshlrev_b32_e32 v74, 16, v68
	v_and_b32_e32 v75, 0xffff0000, v68
	v_lshlrev_b32_e32 v68, 16, v69
	v_and_b32_e32 v69, 0xffff0000, v69
	v_pk_add_f32 v[66:67], v[62:63], v[66:67]
	v_pk_add_f32 v[72:73], v[60:61], v[72:73]
	v_pk_add_f32 v[68:69], v[58:59], v[68:69]
	v_pk_add_f32 v[74:75], v[56:57], v[74:75]
	v_cvt_pk_bf16_f32 v56, v72, v73
	v_cvt_pk_bf16_f32 v57, v66, v67
	v_mul_f32_e32 v73, v73, v73
	v_cvt_pk_bf16_f32 v58, v74, v75
	v_cvt_pk_bf16_f32 v59, v68, v69
	v_mul_f32_e32 v67, v67, v67
	v_mul_f32_e32 v75, v75, v75
	v_fmac_f32_e32 v73, v72, v72
	v_fmac_f32_e32 v67, v66, v66
	v_mul_f32_e32 v69, v69, v69
	v_fmac_f32_e32 v75, v74, v74
	v_add_f32_e32 v66, v73, v67
	v_fmac_f32_e32 v69, v68, v68
	v_add_f32_e32 v66, v75, v66
	v_add_f32_e32 v72, v69, v66
	global_store_dwordx4 v[70:71], v[56:59], off
	s_waitcnt vmcnt(15)
	v_mov_b64 v[60:61], v[210:211]
	v_mov_b64 v[62:63], v[212:213]
	v_lshlrev_b32_e32 v66, 16, v60
	v_and_b32_e32 v67, 0xffff0000, v60
	v_lshlrev_b32_e32 v60, 16, v61
	v_and_b32_e32 v61, 0xffff0000, v61
	v_lshlrev_b32_e32 v68, 16, v62
	v_and_b32_e32 v69, 0xffff0000, v62
	v_lshlrev_b32_e32 v62, 16, v63
	v_and_b32_e32 v63, 0xffff0000, v63
	v_pk_add_f32 v[54:55], v[54:55], v[60:61]
	v_pk_add_f32 v[52:53], v[52:53], v[66:67]
	v_pk_add_f32 v[60:61], v[50:51], v[62:63]
	v_pk_add_f32 v[62:63], v[48:49], v[68:69]
	v_mul_f32_e32 v48, v53, v53
	v_mul_f32_e32 v49, v55, v55
	v_mul_f32_e32 v50, v63, v63
	v_fmac_f32_e32 v48, v52, v52
	v_fmac_f32_e32 v49, v54, v54
	v_mul_f32_e32 v51, v61, v61
	v_fmac_f32_e32 v50, v62, v62
	v_add_f32_e32 v48, v48, v49
	v_add_f32_e32 v48, v50, v48
	v_fmac_f32_e32 v51, v60, v60
	v_add_f32_e32 v48, v51, v48
	v_add_f32_e32 v48, v72, v48
	ds_bpermute_b32 v49, v114, v48
	v_cvt_pk_bf16_f32 v50, v52, v53
	v_cvt_pk_bf16_f32 v51, v54, v55
	v_cvt_pk_bf16_f32 v52, v62, v63
	v_cvt_pk_bf16_f32 v53, v60, v61
	s_waitcnt lgkmcnt(0)
	v_add_f32_e32 v48, v48, v49
	ds_bpermute_b32 v49, v115, v48
	global_store_dwordx4 v[70:71], v[50:53], off offset:256
	s_and_saveexec_b64 s[0:1], s[34:35]
	s_cbranch_execz .LBB0_3630
	s_waitcnt lgkmcnt(0)
	v_add_f32_e32 v50, v48, v49
	s_lshl_b32 s22, s9, 2
	v_lshlrev_b64 v[48:49], 7, v[64:65]
	s_ashr_i32 s23, s22, 31
	v_lshl_add_u64 v[48:49], s[44:45], 0, v[48:49]
	v_lshl_add_u64 v[48:49], s[22:23], 2, v[48:49]
	s_lshl_b32 s40, s60, 2
	v_lshl_add_u64 v[48:49], v[48:49], 0, s[40:41]
	global_store_dword v[48:49], v50, off
.LBB0_3630:
	s_or_b64 exec, exec, s[0:1]
	v_add_u32_e32 v48, 0x90, v140
	s_waitcnt lgkmcnt(0)
	v_ashrrev_i32_e32 v49, 31, v48
	v_lshlrev_b64 v[50:51], 12, v[48:49]
	v_lshl_add_u64 v[50:51], s[38:39], 0, v[50:51]
	v_lshl_add_u64 v[54:55], v[138:139], 1, v[50:51]
	s_waitcnt vmcnt(15)
	v_mov_b64 v[50:51], v[214:215]
	v_mov_b64 v[52:53], v[216:217]
	v_lshlrev_b32_e32 v56, 16, v50
	v_and_b32_e32 v57, 0xffff0000, v50
	v_lshlrev_b32_e32 v50, 16, v51
	v_and_b32_e32 v51, 0xffff0000, v51
	v_lshlrev_b32_e32 v58, 16, v52
	v_and_b32_e32 v59, 0xffff0000, v52
	v_lshlrev_b32_e32 v52, 16, v53
	v_and_b32_e32 v53, 0xffff0000, v53
	v_pk_add_f32 v[50:51], v[46:47], v[50:51]
	v_pk_add_f32 v[56:57], v[44:45], v[56:57]
	v_pk_add_f32 v[52:53], v[42:43], v[52:53]
	v_pk_add_f32 v[58:59], v[40:41], v[58:59]
	v_cvt_pk_bf16_f32 v40, v56, v57
	v_cvt_pk_bf16_f32 v41, v50, v51
	v_mul_f32_e32 v57, v57, v57
	v_cvt_pk_bf16_f32 v42, v58, v59
	v_cvt_pk_bf16_f32 v43, v52, v53
	v_mul_f32_e32 v51, v51, v51
	v_mul_f32_e32 v59, v59, v59
	v_fmac_f32_e32 v57, v56, v56
	v_fmac_f32_e32 v51, v50, v50
	v_mul_f32_e32 v53, v53, v53
	v_fmac_f32_e32 v59, v58, v58
	v_add_f32_e32 v50, v57, v51
	v_fmac_f32_e32 v53, v52, v52
	v_add_f32_e32 v50, v59, v50
	v_add_f32_e32 v56, v53, v50
	global_store_dwordx4 v[54:55], v[40:43], off
	s_waitcnt vmcnt(15)
	v_mov_b64 v[44:45], v[218:219]
	v_mov_b64 v[46:47], v[220:221]
	v_lshlrev_b32_e32 v50, 16, v44
	v_and_b32_e32 v51, 0xffff0000, v44
	v_lshlrev_b32_e32 v44, 16, v45
	v_and_b32_e32 v45, 0xffff0000, v45
	v_lshlrev_b32_e32 v52, 16, v46
	v_and_b32_e32 v53, 0xffff0000, v46
	v_lshlrev_b32_e32 v46, 16, v47
	v_and_b32_e32 v47, 0xffff0000, v47
	v_pk_add_f32 v[38:39], v[38:39], v[44:45]
	v_pk_add_f32 v[36:37], v[36:37], v[50:51]
	v_pk_add_f32 v[44:45], v[34:35], v[46:47]
	v_pk_add_f32 v[46:47], v[32:33], v[52:53]
	v_mul_f32_e32 v32, v37, v37
	v_mul_f32_e32 v33, v39, v39
	v_mul_f32_e32 v34, v47, v47
	v_fmac_f32_e32 v32, v36, v36
	v_fmac_f32_e32 v33, v38, v38
	v_mul_f32_e32 v35, v45, v45
	v_fmac_f32_e32 v34, v46, v46
	v_add_f32_e32 v32, v32, v33
	v_add_f32_e32 v32, v34, v32
	v_fmac_f32_e32 v35, v44, v44
	v_add_f32_e32 v32, v35, v32
	v_add_f32_e32 v32, v56, v32
	ds_bpermute_b32 v33, v114, v32
	v_cvt_pk_bf16_f32 v34, v36, v37
	v_cvt_pk_bf16_f32 v35, v38, v39
	v_cvt_pk_bf16_f32 v36, v46, v47
	v_cvt_pk_bf16_f32 v37, v44, v45
	s_waitcnt lgkmcnt(0)
	v_add_f32_e32 v32, v32, v33
	ds_bpermute_b32 v33, v115, v32
	global_store_dwordx4 v[54:55], v[34:37], off offset:256
	s_and_saveexec_b64 s[0:1], s[34:35]
	s_cbranch_execz .LBB0_3632
	s_waitcnt lgkmcnt(0)
	v_add_f32_e32 v34, v32, v33
	s_lshl_b32 s22, s9, 2
	v_lshlrev_b64 v[32:33], 7, v[48:49]
	s_ashr_i32 s23, s22, 31
	v_lshl_add_u64 v[32:33], s[44:45], 0, v[32:33]
	v_lshl_add_u64 v[32:33], s[22:23], 2, v[32:33]
	s_lshl_b32 s40, s60, 2
	v_lshl_add_u64 v[32:33], v[32:33], 0, s[40:41]
	global_store_dword v[32:33], v34, off
.LBB0_3632:
	s_or_b64 exec, exec, s[0:1]
	v_add_u32_e32 v32, 0xa0, v140
	s_waitcnt lgkmcnt(0)
	v_ashrrev_i32_e32 v33, 31, v32
	v_lshlrev_b64 v[34:35], 12, v[32:33]
	v_lshl_add_u64 v[34:35], s[38:39], 0, v[34:35]
	v_lshl_add_u64 v[38:39], v[138:139], 1, v[34:35]
	s_waitcnt vmcnt(14)
	v_mov_b64 v[34:35], v[170:171]
	v_mov_b64 v[36:37], v[172:173]
	v_lshlrev_b32_e32 v40, 16, v34
	v_and_b32_e32 v41, 0xffff0000, v34
	v_lshlrev_b32_e32 v34, 16, v35
	v_and_b32_e32 v35, 0xffff0000, v35
	v_lshlrev_b32_e32 v42, 16, v36
	v_and_b32_e32 v43, 0xffff0000, v36
	v_lshlrev_b32_e32 v36, 16, v37
	v_and_b32_e32 v37, 0xffff0000, v37
	v_pk_add_f32 v[34:35], v[30:31], v[34:35]
	v_pk_add_f32 v[40:41], v[28:29], v[40:41]
	v_pk_add_f32 v[36:37], v[26:27], v[36:37]
	v_pk_add_f32 v[42:43], v[24:25], v[42:43]
	v_cvt_pk_bf16_f32 v24, v40, v41
	v_cvt_pk_bf16_f32 v25, v34, v35
	v_mul_f32_e32 v41, v41, v41
	v_cvt_pk_bf16_f32 v26, v42, v43
	v_cvt_pk_bf16_f32 v27, v36, v37
	v_mul_f32_e32 v35, v35, v35
	v_mul_f32_e32 v43, v43, v43
	v_fmac_f32_e32 v41, v40, v40
	v_fmac_f32_e32 v35, v34, v34
	v_mul_f32_e32 v37, v37, v37
	v_fmac_f32_e32 v43, v42, v42
	v_add_f32_e32 v34, v41, v35
	v_fmac_f32_e32 v37, v36, v36
	v_add_f32_e32 v34, v43, v34
	v_add_f32_e32 v40, v37, v34
	global_store_dwordx4 v[38:39], v[24:27], off
	s_waitcnt vmcnt(14)
	v_mov_b64 v[28:29], v[174:175]
	v_mov_b64 v[30:31], v[176:177]
	v_lshlrev_b32_e32 v34, 16, v28
	v_and_b32_e32 v35, 0xffff0000, v28
	v_lshlrev_b32_e32 v28, 16, v29
	v_and_b32_e32 v29, 0xffff0000, v29
	v_lshlrev_b32_e32 v36, 16, v30
	v_and_b32_e32 v37, 0xffff0000, v30
	v_lshlrev_b32_e32 v30, 16, v31
	v_and_b32_e32 v31, 0xffff0000, v31
	v_pk_add_f32 v[22:23], v[22:23], v[28:29]
	v_pk_add_f32 v[20:21], v[20:21], v[34:35]
	v_pk_add_f32 v[28:29], v[18:19], v[30:31]
	v_pk_add_f32 v[30:31], v[16:17], v[36:37]
	v_mul_f32_e32 v16, v21, v21
	v_mul_f32_e32 v17, v23, v23
	v_mul_f32_e32 v18, v31, v31
	v_fmac_f32_e32 v16, v20, v20
	v_fmac_f32_e32 v17, v22, v22
	v_mul_f32_e32 v19, v29, v29
	v_fmac_f32_e32 v18, v30, v30
	v_add_f32_e32 v16, v16, v17
	v_add_f32_e32 v16, v18, v16
	v_fmac_f32_e32 v19, v28, v28
	v_add_f32_e32 v16, v19, v16
	v_add_f32_e32 v16, v40, v16
	ds_bpermute_b32 v17, v114, v16
	v_cvt_pk_bf16_f32 v18, v20, v21
	v_cvt_pk_bf16_f32 v19, v22, v23
	v_cvt_pk_bf16_f32 v20, v30, v31
	v_cvt_pk_bf16_f32 v21, v28, v29
	s_waitcnt lgkmcnt(0)
	v_add_f32_e32 v16, v16, v17
	ds_bpermute_b32 v17, v115, v16
	global_store_dwordx4 v[38:39], v[18:21], off offset:256
	s_and_saveexec_b64 s[0:1], s[34:35]
	s_cbranch_execz .LBB0_3634
	s_waitcnt lgkmcnt(0)
	v_add_f32_e32 v18, v16, v17
	s_lshl_b32 s22, s9, 2
	v_lshlrev_b64 v[16:17], 7, v[32:33]
	s_ashr_i32 s23, s22, 31
	v_lshl_add_u64 v[16:17], s[44:45], 0, v[16:17]
	v_lshl_add_u64 v[16:17], s[22:23], 2, v[16:17]
	s_lshl_b32 s40, s60, 2
	v_lshl_add_u64 v[16:17], v[16:17], 0, s[40:41]
	global_store_dword v[16:17], v18, off
.LBB0_3634:
	s_or_b64 exec, exec, s[0:1]
	v_add_u32_e32 v16, 0xb0, v140
	s_waitcnt lgkmcnt(0)
	v_ashrrev_i32_e32 v17, 31, v16
	v_lshlrev_b64 v[18:19], 12, v[16:17]
	v_lshl_add_u64 v[18:19], s[38:39], 0, v[18:19]
	v_lshl_add_u64 v[22:23], v[138:139], 1, v[18:19]
	s_waitcnt vmcnt(12)
	v_mov_b64 v[18:19], v[178:179]
	v_mov_b64 v[20:21], v[180:181]
	v_lshlrev_b32_e32 v24, 16, v18
	v_and_b32_e32 v25, 0xffff0000, v18
	v_lshlrev_b32_e32 v18, 16, v19
	v_and_b32_e32 v19, 0xffff0000, v19
	v_lshlrev_b32_e32 v26, 16, v20
	v_and_b32_e32 v27, 0xffff0000, v20
	v_lshlrev_b32_e32 v20, 16, v21
	v_and_b32_e32 v21, 0xffff0000, v21
	v_pk_add_f32 v[18:19], v[14:15], v[18:19]
	v_pk_add_f32 v[24:25], v[12:13], v[24:25]
	v_pk_add_f32 v[20:21], v[10:11], v[20:21]
	v_pk_add_f32 v[26:27], v[8:9], v[26:27]
	v_cvt_pk_bf16_f32 v8, v24, v25
	v_cvt_pk_bf16_f32 v9, v18, v19
	v_mul_f32_e32 v25, v25, v25
	v_cvt_pk_bf16_f32 v10, v26, v27
	v_cvt_pk_bf16_f32 v11, v20, v21
	v_mul_f32_e32 v19, v19, v19
	v_mul_f32_e32 v27, v27, v27
	v_fmac_f32_e32 v25, v24, v24
	v_fmac_f32_e32 v19, v18, v18
	v_mul_f32_e32 v21, v21, v21
	v_fmac_f32_e32 v27, v26, v26
	v_add_f32_e32 v18, v25, v19
	v_fmac_f32_e32 v21, v20, v20
	v_add_f32_e32 v18, v27, v18
	v_add_f32_e32 v24, v21, v18
	global_store_dwordx4 v[22:23], v[8:11], off
	s_waitcnt vmcnt(12)
	v_mov_b64 v[12:13], v[182:183]
	v_mov_b64 v[14:15], v[184:185]
	v_lshlrev_b32_e32 v18, 16, v12
	v_and_b32_e32 v19, 0xffff0000, v12
	v_lshlrev_b32_e32 v12, 16, v13
	v_and_b32_e32 v13, 0xffff0000, v13
	v_lshlrev_b32_e32 v20, 16, v14
	v_and_b32_e32 v21, 0xffff0000, v14
	v_lshlrev_b32_e32 v14, 16, v15
	v_and_b32_e32 v15, 0xffff0000, v15
	v_pk_add_f32 v[6:7], v[6:7], v[12:13]
	v_pk_add_f32 v[4:5], v[4:5], v[18:19]
	v_pk_add_f32 v[12:13], v[2:3], v[14:15]
	v_pk_add_f32 v[14:15], v[0:1], v[20:21]
	v_mul_f32_e32 v0, v5, v5
	v_mul_f32_e32 v1, v7, v7
	v_mul_f32_e32 v2, v15, v15
	v_fmac_f32_e32 v0, v4, v4
	v_fmac_f32_e32 v1, v6, v6
	v_mul_f32_e32 v3, v13, v13
	v_fmac_f32_e32 v2, v14, v14
	v_add_f32_e32 v0, v0, v1
	v_add_f32_e32 v0, v2, v0
	v_fmac_f32_e32 v3, v12, v12
	v_add_f32_e32 v0, v3, v0
	v_add_f32_e32 v0, v24, v0
	ds_bpermute_b32 v1, v114, v0
	v_cvt_pk_bf16_f32 v2, v4, v5
	v_cvt_pk_bf16_f32 v3, v6, v7
	v_cvt_pk_bf16_f32 v4, v14, v15
	v_cvt_pk_bf16_f32 v5, v12, v13
	s_waitcnt lgkmcnt(0)
	v_add_f32_e32 v0, v0, v1
	ds_bpermute_b32 v1, v115, v0
	global_store_dwordx4 v[22:23], v[2:5], off offset:256
	s_and_saveexec_b64 s[0:1], s[34:35]
	s_cbranch_execz .LBB0_3636
	s_waitcnt lgkmcnt(0)
	v_add_f32_e32 v2, v0, v1
	s_lshl_b32 s22, s9, 2
	v_lshlrev_b64 v[0:1], 7, v[16:17]
	s_ashr_i32 s23, s22, 31
	v_lshl_add_u64 v[0:1], s[44:45], 0, v[0:1]
	v_lshl_add_u64 v[0:1], s[22:23], 2, v[0:1]
	s_lshl_b32 s40, s60, 2
	v_lshl_add_u64 v[0:1], v[0:1], 0, s[40:41]
	global_store_dword v[0:1], v2, off

.LBB0_7640:
	v_add_u32_e32 v140, s26, v142
	v_lshlrev_b32_e32 v200, 12, v140
	v_lshl_add_u32 v200, v138, 1, v200
	global_load_dwordx4 v[168:171], v200, s[38:39]
	global_load_dwordx4 v[172:175], v200, s[38:39] offset:256
	s_add_u32 s98, s38, 0x10000
	s_addc_u32 s99, s39, 0
	global_load_dwordx4 v[176:179], v200, s[98:99]
	global_load_dwordx4 v[180:183], v200, s[98:99] offset:256
	s_add_u32 s98, s38, 0x20000
	s_addc_u32 s99, s39, 0
	global_load_dwordx4 v[184:187], v200, s[98:99]
	global_load_dwordx4 v[188:191], v200, s[98:99] offset:256
	s_add_u32 s98, s38, 0x30000
	s_addc_u32 s99, s39, 0
	global_load_dwordx4 v[192:195], v200, s[98:99]
	global_load_dwordx4 v[196:199], v200, s[98:99] offset:256
	s_add_u32 s98, s38, 0x80000
	s_addc_u32 s99, s39, 0
	global_load_dwordx4 v[206:209], v200, s[98:99]
	global_load_dwordx4 v[210:213], v200, s[98:99] offset:256
	s_add_u32 s98, s38, 0x90000
	s_addc_u32 s99, s39, 0
	global_load_dwordx4 v[214:217], v200, s[98:99]
	global_load_dwordx4 v[218:221], v200, s[98:99] offset:256
	v_ashrrev_i32_e32 v141, 31, v140
	v_lshlrev_b64 v[156:157], 12, v[140:141]
	v_lshl_add_u64 v[156:157], s[38:39], 0, v[156:157]
	v_lshl_add_u64 v[160:161], v[138:139], 1, v[156:157]
	s_waitcnt vmcnt(11)
	v_mov_b64 v[156:157], v[168:169]
	v_mov_b64 v[158:159], v[170:171]
	v_lshlrev_b32_e32 v162, 16, v156
	v_and_b32_e32 v163, 0xffff0000, v156
	v_lshlrev_b32_e32 v156, 16, v157
	v_and_b32_e32 v157, 0xffff0000, v157
	v_lshlrev_b32_e32 v166, 16, v158
	v_and_b32_e32 v167, 0xffff0000, v158
	v_lshlrev_b32_e32 v158, 16, v159
	v_and_b32_e32 v159, 0xffff0000, v159
	v_pk_add_f32 v[126:127], v[126:127], v[156:157]
	v_pk_add_f32 v[124:125], v[124:125], v[162:163]
	v_pk_add_f32 v[156:157], v[122:123], v[158:159]
	v_pk_add_f32 v[158:159], v[120:121], v[166:167]
	v_cvt_pk_bf16_f32 v120, v124, v125
	v_cvt_pk_bf16_f32 v121, v126, v127
	s_nop 0
	v_cvt_pk_bf16_f32 v122, v158, v159
	v_cvt_pk_bf16_f32 v123, v156, v157
	global_store_dwordx4 v[160:161], v[120:123], off
	s_nop 1
	v_mul_f32_e32 v120, v125, v125
	v_mul_f32_e32 v121, v127, v127
	v_fmac_f32_e32 v120, v124, v124
	v_fmac_f32_e32 v121, v126, v126
	v_add_f32_e32 v120, v120, v121
	v_mul_f32_e32 v121, v159, v159
	v_fmac_f32_e32 v121, v158, v158
	v_add_f32_e32 v120, v121, v120
	v_mul_f32_e32 v121, v157, v157
	v_fmac_f32_e32 v121, v156, v156
	v_add_f32_e32 v155, v121, v120
	s_waitcnt vmcnt(11)
	v_mov_b64 v[120:121], v[172:173]
	v_mov_b64 v[122:123], v[174:175]
	s_add_u32 s98, s38, 0xa0000
	s_addc_u32 s99, s39, 0
	global_load_dwordx4 v[168:171], v200, s[98:99]
	global_load_dwordx4 v[172:175], v200, s[98:99] offset:256
	v_lshlrev_b32_e32 v124, 16, v120
	v_and_b32_e32 v125, 0xffff0000, v120
	v_lshlrev_b32_e32 v120, 16, v121
	v_and_b32_e32 v121, 0xffff0000, v121
	v_lshlrev_b32_e32 v126, 16, v122
	v_and_b32_e32 v127, 0xffff0000, v122
	v_lshlrev_b32_e32 v122, 16, v123
	v_and_b32_e32 v123, 0xffff0000, v123
	v_pk_add_f32 v[118:119], v[118:119], v[120:121]
	v_pk_add_f32 v[116:117], v[116:117], v[124:125]
	v_pk_add_f32 v[120:121], v[114:115], v[122:123]
	v_pk_add_f32 v[122:123], v[112:113], v[126:127]
	v_cvt_pk_bf16_f32 v112, v116, v117
	v_cvt_pk_bf16_f32 v113, v118, v119
	s_nop 0
	v_cvt_pk_bf16_f32 v114, v122, v123
	v_cvt_pk_bf16_f32 v115, v120, v121
	global_store_dwordx4 v[160:161], v[112:115], off offset:256
	s_nop 1
	v_mul_f32_e32 v112, v117, v117
	v_mul_f32_e32 v113, v119, v119
	v_fmac_f32_e32 v112, v116, v116
	v_fmac_f32_e32 v113, v118, v118
	v_add_f32_e32 v112, v112, v113
	v_mul_f32_e32 v113, v123, v123
	v_fmac_f32_e32 v113, v122, v122
	v_add_f32_e32 v112, v113, v112
	v_mul_f32_e32 v113, v121, v121
	v_fmac_f32_e32 v113, v120, v120
	v_and_b32_e32 v114, 64, v204
	v_add_f32_e32 v112, v113, v112
	v_xor_b32_e32 v113, 16, v204
	v_add_u32_e32 v115, 64, v114
	v_cmp_lt_i32_e32 vcc, v113, v115
	v_add_f32_e32 v112, v155, v112
	s_nop 0
	v_cndmask_b32_e32 v113, v204, v113, vcc
	v_lshlrev_b32_e32 v114, 2, v113
	ds_bpermute_b32 v113, v114, v112
	s_waitcnt lgkmcnt(0)
	v_add_f32_e32 v112, v112, v113
	v_xor_b32_e32 v113, 32, v204
	v_cmp_lt_i32_e32 vcc, v113, v115
	s_nop 1
	v_cndmask_b32_e32 v113, v204, v113, vcc
	v_lshlrev_b32_e32 v115, 2, v113
	ds_bpermute_b32 v113, v115, v112
	s_and_saveexec_b64 s[0:1], s[34:35]
	s_cbranch_execz .LBB0_7642
	s_waitcnt lgkmcnt(0)
	v_add_f32_e32 v116, v112, v113
	s_lshl_b32 s22, s70, 2
	v_lshlrev_b64 v[112:113], 7, v[140:141]
	s_ashr_i32 s23, s22, 31
	v_lshl_add_u64 v[112:113], s[48:49], 0, v[112:113]
	v_lshl_add_u64 v[112:113], s[22:23], 2, v[112:113]
	s_lshl_b32 s44, s83, 2
	v_lshl_add_u64 v[112:113], v[112:113], 0, s[44:45]
	global_store_dword v[112:113], v116, off
.LBB0_7642:
	s_or_b64 exec, exec, s[0:1]
	v_or_b32_e32 v112, 16, v140
	s_waitcnt lgkmcnt(0)
	v_ashrrev_i32_e32 v113, 31, v112
	v_lshlrev_b64 v[116:117], 12, v[112:113]
	v_lshl_add_u64 v[116:117], s[38:39], 0, v[116:117]
	v_lshl_add_u64 v[120:121], v[138:139], 1, v[116:117]
	s_waitcnt vmcnt(13)
	v_mov_b64 v[116:117], v[176:177]
	v_mov_b64 v[118:119], v[178:179]
	v_lshlrev_b32_e32 v122, 16, v116
	v_and_b32_e32 v123, 0xffff0000, v116
	v_lshlrev_b32_e32 v116, 16, v117
	v_and_b32_e32 v117, 0xffff0000, v117
	v_lshlrev_b32_e32 v124, 16, v118
	v_and_b32_e32 v125, 0xffff0000, v118
	v_lshlrev_b32_e32 v118, 16, v119
	v_and_b32_e32 v119, 0xffff0000, v119
	v_pk_add_f32 v[116:117], v[110:111], v[116:117]
	v_pk_add_f32 v[122:123], v[108:109], v[122:123]
	v_pk_add_f32 v[118:119], v[106:107], v[118:119]
	v_pk_add_f32 v[124:125], v[104:105], v[124:125]
	v_cvt_pk_bf16_f32 v104, v122, v123
	v_cvt_pk_bf16_f32 v105, v116, v117
	v_mul_f32_e32 v123, v123, v123
	v_cvt_pk_bf16_f32 v106, v124, v125
	v_cvt_pk_bf16_f32 v107, v118, v119
	v_mul_f32_e32 v117, v117, v117
	v_mul_f32_e32 v125, v125, v125
	v_fmac_f32_e32 v123, v122, v122
	v_fmac_f32_e32 v117, v116, v116
	v_mul_f32_e32 v119, v119, v119
	v_fmac_f32_e32 v125, v124, v124
	v_add_f32_e32 v116, v123, v117
	v_fmac_f32_e32 v119, v118, v118
	v_add_f32_e32 v116, v125, v116
	v_add_f32_e32 v122, v119, v116
	global_store_dwordx4 v[120:121], v[104:107], off
	s_waitcnt vmcnt(13)
	v_mov_b64 v[108:109], v[180:181]
	v_mov_b64 v[110:111], v[182:183]
	s_add_u32 s98, s38, 0xb0000
	s_addc_u32 s99, s39, 0
	global_load_dwordx4 v[176:179], v200, s[98:99]
	global_load_dwordx4 v[180:183], v200, s[98:99] offset:256
	v_lshlrev_b32_e32 v116, 16, v108
	v_and_b32_e32 v117, 0xffff0000, v108
	v_lshlrev_b32_e32 v108, 16, v109
	v_and_b32_e32 v109, 0xffff0000, v109
	v_lshlrev_b32_e32 v118, 16, v110
	v_and_b32_e32 v119, 0xffff0000, v110
	v_lshlrev_b32_e32 v110, 16, v111
	v_and_b32_e32 v111, 0xffff0000, v111
	v_pk_add_f32 v[102:103], v[102:103], v[108:109]
	v_pk_add_f32 v[100:101], v[100:101], v[116:117]
	v_pk_add_f32 v[108:109], v[98:99], v[110:111]
	v_pk_add_f32 v[110:111], v[96:97], v[118:119]
	v_mul_f32_e32 v96, v101, v101
	v_mul_f32_e32 v97, v103, v103
	v_mul_f32_e32 v98, v111, v111
	v_fmac_f32_e32 v96, v100, v100
	v_fmac_f32_e32 v97, v102, v102
	v_mul_f32_e32 v99, v109, v109
	v_fmac_f32_e32 v98, v110, v110
	v_add_f32_e32 v96, v96, v97
	v_add_f32_e32 v96, v98, v96
	v_fmac_f32_e32 v99, v108, v108
	v_add_f32_e32 v96, v99, v96
	v_add_f32_e32 v96, v122, v96
	ds_bpermute_b32 v97, v114, v96
	v_cvt_pk_bf16_f32 v98, v100, v101
	v_cvt_pk_bf16_f32 v99, v102, v103
	v_cvt_pk_bf16_f32 v100, v110, v111
	v_cvt_pk_bf16_f32 v101, v108, v109
	s_waitcnt lgkmcnt(0)
	v_add_f32_e32 v96, v96, v97
	ds_bpermute_b32 v97, v115, v96
	global_store_dwordx4 v[120:121], v[98:101], off offset:256
	s_and_saveexec_b64 s[0:1], s[34:35]
	s_cbranch_execz .LBB0_7644
	s_waitcnt lgkmcnt(0)
	v_add_f32_e32 v98, v96, v97
	s_lshl_b32 s22, s70, 2
	v_lshlrev_b64 v[96:97], 7, v[112:113]
	s_ashr_i32 s23, s22, 31
	v_lshl_add_u64 v[96:97], s[48:49], 0, v[96:97]
	v_lshl_add_u64 v[96:97], s[22:23], 2, v[96:97]
	s_lshl_b32 s44, s83, 2
	v_lshl_add_u64 v[96:97], v[96:97], 0, s[44:45]
	global_store_dword v[96:97], v98, off
.LBB0_7644:
	s_or_b64 exec, exec, s[0:1]
	v_or_b32_e32 v96, 32, v140
	s_waitcnt lgkmcnt(0)
	v_ashrrev_i32_e32 v97, 31, v96
	v_lshlrev_b64 v[98:99], 12, v[96:97]
	v_lshl_add_u64 v[98:99], s[38:39], 0, v[98:99]
	v_lshl_add_u64 v[102:103], v[138:139], 1, v[98:99]
	s_waitcnt vmcnt(15)
	v_mov_b64 v[98:99], v[184:185]
	v_mov_b64 v[100:101], v[186:187]
	v_lshlrev_b32_e32 v104, 16, v98
	v_and_b32_e32 v105, 0xffff0000, v98
	v_lshlrev_b32_e32 v98, 16, v99
	v_and_b32_e32 v99, 0xffff0000, v99
	v_lshlrev_b32_e32 v106, 16, v100
	v_and_b32_e32 v107, 0xffff0000, v100
	v_lshlrev_b32_e32 v100, 16, v101
	v_and_b32_e32 v101, 0xffff0000, v101
	v_pk_add_f32 v[98:99], v[94:95], v[98:99]
	v_pk_add_f32 v[104:105], v[92:93], v[104:105]
	v_pk_add_f32 v[100:101], v[90:91], v[100:101]
	v_pk_add_f32 v[106:107], v[88:89], v[106:107]
	v_cvt_pk_bf16_f32 v88, v104, v105
	v_cvt_pk_bf16_f32 v89, v98, v99
	v_mul_f32_e32 v105, v105, v105
	v_cvt_pk_bf16_f32 v90, v106, v107
	v_cvt_pk_bf16_f32 v91, v100, v101
	v_mul_f32_e32 v99, v99, v99
	v_mul_f32_e32 v107, v107, v107
	v_fmac_f32_e32 v105, v104, v104
	v_fmac_f32_e32 v99, v98, v98
	v_mul_f32_e32 v101, v101, v101
	v_fmac_f32_e32 v107, v106, v106
	v_add_f32_e32 v98, v105, v99
	v_fmac_f32_e32 v101, v100, v100
	v_add_f32_e32 v98, v107, v98
	v_add_f32_e32 v104, v101, v98
	global_store_dwordx4 v[102:103], v[88:91], off
	s_waitcnt vmcnt(15)
	v_mov_b64 v[92:93], v[188:189]
	v_mov_b64 v[94:95], v[190:191]
	v_lshlrev_b32_e32 v98, 16, v92
	v_and_b32_e32 v99, 0xffff0000, v92
	v_lshlrev_b32_e32 v92, 16, v93
	v_and_b32_e32 v93, 0xffff0000, v93
	v_lshlrev_b32_e32 v100, 16, v94
	v_and_b32_e32 v101, 0xffff0000, v94
	v_lshlrev_b32_e32 v94, 16, v95
	v_and_b32_e32 v95, 0xffff0000, v95
	v_pk_add_f32 v[86:87], v[86:87], v[92:93]
	v_pk_add_f32 v[84:85], v[84:85], v[98:99]
	v_pk_add_f32 v[92:93], v[82:83], v[94:95]
	v_pk_add_f32 v[94:95], v[80:81], v[100:101]
	v_mul_f32_e32 v80, v85, v85
	v_mul_f32_e32 v81, v87, v87
	v_mul_f32_e32 v82, v95, v95
	v_fmac_f32_e32 v80, v84, v84
	v_fmac_f32_e32 v81, v86, v86
	v_mul_f32_e32 v83, v93, v93
	v_fmac_f32_e32 v82, v94, v94
	v_add_f32_e32 v80, v80, v81
	v_add_f32_e32 v80, v82, v80
	v_fmac_f32_e32 v83, v92, v92
	v_add_f32_e32 v80, v83, v80
	v_add_f32_e32 v80, v104, v80
	ds_bpermute_b32 v81, v114, v80
	v_cvt_pk_bf16_f32 v82, v84, v85
	v_cvt_pk_bf16_f32 v83, v86, v87
	v_cvt_pk_bf16_f32 v84, v94, v95
	v_cvt_pk_bf16_f32 v85, v92, v93
	s_waitcnt lgkmcnt(0)
	v_add_f32_e32 v80, v80, v81
	ds_bpermute_b32 v81, v115, v80
	global_store_dwordx4 v[102:103], v[82:85], off offset:256
	s_and_saveexec_b64 s[0:1], s[34:35]
	s_cbranch_execz .LBB0_7646
	s_waitcnt lgkmcnt(0)
	v_add_f32_e32 v82, v80, v81
	s_lshl_b32 s22, s70, 2
	v_lshlrev_b64 v[80:81], 7, v[96:97]
	s_ashr_i32 s23, s22, 31
	v_lshl_add_u64 v[80:81], s[48:49], 0, v[80:81]
	v_lshl_add_u64 v[80:81], s[22:23], 2, v[80:81]
	s_lshl_b32 s44, s83, 2
	v_lshl_add_u64 v[80:81], v[80:81], 0, s[44:45]
	global_store_dword v[80:81], v82, off
.LBB0_7646:
	s_or_b64 exec, exec, s[0:1]
	v_or_b32_e32 v80, 48, v140
	s_waitcnt lgkmcnt(0)
	v_ashrrev_i32_e32 v81, 31, v80
	v_lshlrev_b64 v[82:83], 12, v[80:81]
	v_lshl_add_u64 v[82:83], s[38:39], 0, v[82:83]
	v_lshl_add_u64 v[86:87], v[138:139], 1, v[82:83]
	s_waitcnt vmcnt(15)
	v_mov_b64 v[82:83], v[192:193]
	v_mov_b64 v[84:85], v[194:195]
	v_lshlrev_b32_e32 v88, 16, v82
	v_and_b32_e32 v89, 0xffff0000, v82
	v_lshlrev_b32_e32 v82, 16, v83
	v_and_b32_e32 v83, 0xffff0000, v83
	v_lshlrev_b32_e32 v90, 16, v84
	v_and_b32_e32 v91, 0xffff0000, v84
	v_lshlrev_b32_e32 v84, 16, v85
	v_and_b32_e32 v85, 0xffff0000, v85
	v_pk_add_f32 v[82:83], v[78:79], v[82:83]
	v_pk_add_f32 v[88:89], v[76:77], v[88:89]
	v_pk_add_f32 v[84:85], v[74:75], v[84:85]
	v_pk_add_f32 v[90:91], v[72:73], v[90:91]
	v_cvt_pk_bf16_f32 v72, v88, v89
	v_cvt_pk_bf16_f32 v73, v82, v83
	v_mul_f32_e32 v89, v89, v89
	v_cvt_pk_bf16_f32 v74, v90, v91
	v_cvt_pk_bf16_f32 v75, v84, v85
	v_mul_f32_e32 v83, v83, v83
	v_mul_f32_e32 v91, v91, v91
	v_fmac_f32_e32 v89, v88, v88
	v_fmac_f32_e32 v83, v82, v82
	v_mul_f32_e32 v85, v85, v85
	v_fmac_f32_e32 v91, v90, v90
	v_add_f32_e32 v82, v89, v83
	v_fmac_f32_e32 v85, v84, v84
	v_add_f32_e32 v82, v91, v82
	v_add_f32_e32 v88, v85, v82
	global_store_dwordx4 v[86:87], v[72:75], off
	s_waitcnt vmcnt(15)
	v_mov_b64 v[76:77], v[196:197]
	v_mov_b64 v[78:79], v[198:199]
	v_lshlrev_b32_e32 v82, 16, v76
	v_and_b32_e32 v83, 0xffff0000, v76
	v_lshlrev_b32_e32 v76, 16, v77
	v_and_b32_e32 v77, 0xffff0000, v77
	v_lshlrev_b32_e32 v84, 16, v78
	v_and_b32_e32 v85, 0xffff0000, v78
	v_lshlrev_b32_e32 v78, 16, v79
	v_and_b32_e32 v79, 0xffff0000, v79
	v_pk_add_f32 v[70:71], v[70:71], v[76:77]
	v_pk_add_f32 v[68:69], v[68:69], v[82:83]
	v_pk_add_f32 v[76:77], v[66:67], v[78:79]
	v_pk_add_f32 v[78:79], v[64:65], v[84:85]
	v_mul_f32_e32 v64, v69, v69
	v_mul_f32_e32 v65, v71, v71
	v_mul_f32_e32 v66, v79, v79
	v_fmac_f32_e32 v64, v68, v68
	v_fmac_f32_e32 v65, v70, v70
	v_mul_f32_e32 v67, v77, v77
	v_fmac_f32_e32 v66, v78, v78
	v_add_f32_e32 v64, v64, v65
	v_add_f32_e32 v64, v66, v64
	v_fmac_f32_e32 v67, v76, v76
	v_add_f32_e32 v64, v67, v64
	v_add_f32_e32 v64, v88, v64
	ds_bpermute_b32 v65, v114, v64
	v_cvt_pk_bf16_f32 v66, v68, v69
	v_cvt_pk_bf16_f32 v67, v70, v71
	v_cvt_pk_bf16_f32 v68, v78, v79
	v_cvt_pk_bf16_f32 v69, v76, v77
	s_waitcnt lgkmcnt(0)
	v_add_f32_e32 v64, v64, v65
	ds_bpermute_b32 v65, v115, v64
	global_store_dwordx4 v[86:87], v[66:69], off offset:256
	s_and_saveexec_b64 s[0:1], s[34:35]
	s_cbranch_execz .LBB0_7648
	s_waitcnt lgkmcnt(0)
	v_add_f32_e32 v66, v64, v65
	s_lshl_b32 s22, s70, 2
	v_lshlrev_b64 v[64:65], 7, v[80:81]
	s_ashr_i32 s23, s22, 31
	v_lshl_add_u64 v[64:65], s[48:49], 0, v[64:65]
	v_lshl_add_u64 v[64:65], s[22:23], 2, v[64:65]
	s_lshl_b32 s44, s83, 2
	v_lshl_add_u64 v[64:65], v[64:65], 0, s[44:45]
	global_store_dword v[64:65], v66, off
.LBB0_7648:
	s_or_b64 exec, exec, s[0:1]
	v_add_u32_e32 v64, 0x80, v140
	s_waitcnt lgkmcnt(0)
	v_ashrrev_i32_e32 v65, 31, v64
	v_lshlrev_b64 v[66:67], 12, v[64:65]
	v_lshl_add_u64 v[66:67], s[38:39], 0, v[66:67]
	v_lshl_add_u64 v[70:71], v[138:139], 1, v[66:67]
	s_waitcnt vmcnt(15)
	v_mov_b64 v[66:67], v[206:207]
	v_mov_b64 v[68:69], v[208:209]
	v_lshlrev_b32_e32 v72, 16, v66
	v_and_b32_e32 v73, 0xffff0000, v66
	v_lshlrev_b32_e32 v66, 16, v67
	v_and_b32_e32 v67, 0xffff0000, v67
	v_lshlrev_b32_e32 v74, 16, v68
	v_and_b32_e32 v75, 0xffff0000, v68
	v_lshlrev_b32_e32 v68, 16, v69
	v_and_b32_e32 v69, 0xffff0000, v69
	v_pk_add_f32 v[66:67], v[62:63], v[66:67]
	v_pk_add_f32 v[72:73], v[60:61], v[72:73]
	v_pk_add_f32 v[68:69], v[58:59], v[68:69]
	v_pk_add_f32 v[74:75], v[56:57], v[74:75]
	v_cvt_pk_bf16_f32 v56, v72, v73
	v_cvt_pk_bf16_f32 v57, v66, v67
	v_mul_f32_e32 v73, v73, v73
	v_cvt_pk_bf16_f32 v58, v74, v75
	v_cvt_pk_bf16_f32 v59, v68, v69
	v_mul_f32_e32 v67, v67, v67
	v_mul_f32_e32 v75, v75, v75
	v_fmac_f32_e32 v73, v72, v72
	v_fmac_f32_e32 v67, v66, v66
	v_mul_f32_e32 v69, v69, v69
	v_fmac_f32_e32 v75, v74, v74
	v_add_f32_e32 v66, v73, v67
	v_fmac_f32_e32 v69, v68, v68
	v_add_f32_e32 v66, v75, v66
	v_add_f32_e32 v72, v69, v66
	global_store_dwordx4 v[70:71], v[56:59], off
	s_waitcnt vmcnt(15)
	v_mov_b64 v[60:61], v[210:211]
	v_mov_b64 v[62:63], v[212:213]
	v_lshlrev_b32_e32 v66, 16, v60
	v_and_b32_e32 v67, 0xffff0000, v60
	v_lshlrev_b32_e32 v60, 16, v61
	v_and_b32_e32 v61, 0xffff0000, v61
	v_lshlrev_b32_e32 v68, 16, v62
	v_and_b32_e32 v69, 0xffff0000, v62
	v_lshlrev_b32_e32 v62, 16, v63
	v_and_b32_e32 v63, 0xffff0000, v63
	v_pk_add_f32 v[54:55], v[54:55], v[60:61]
	v_pk_add_f32 v[52:53], v[52:53], v[66:67]
	v_pk_add_f32 v[60:61], v[50:51], v[62:63]
	v_pk_add_f32 v[62:63], v[48:49], v[68:69]
	v_mul_f32_e32 v48, v53, v53
	v_mul_f32_e32 v49, v55, v55
	v_mul_f32_e32 v50, v63, v63
	v_fmac_f32_e32 v48, v52, v52
	v_fmac_f32_e32 v49, v54, v54
	v_mul_f32_e32 v51, v61, v61
	v_fmac_f32_e32 v50, v62, v62
	v_add_f32_e32 v48, v48, v49
	v_add_f32_e32 v48, v50, v48
	v_fmac_f32_e32 v51, v60, v60
	v_add_f32_e32 v48, v51, v48
	v_add_f32_e32 v48, v72, v48
	ds_bpermute_b32 v49, v114, v48
	v_cvt_pk_bf16_f32 v50, v52, v53
	v_cvt_pk_bf16_f32 v51, v54, v55
	v_cvt_pk_bf16_f32 v52, v62, v63
	v_cvt_pk_bf16_f32 v53, v60, v61
	s_waitcnt lgkmcnt(0)
	v_add_f32_e32 v48, v48, v49
	ds_bpermute_b32 v49, v115, v48
	global_store_dwordx4 v[70:71], v[50:53], off offset:256
	s_and_saveexec_b64 s[0:1], s[34:35]
	s_cbranch_execz .LBB0_7650
	s_waitcnt lgkmcnt(0)
	v_add_f32_e32 v50, v48, v49
	s_lshl_b32 s22, s70, 2
	v_lshlrev_b64 v[48:49], 7, v[64:65]
	s_ashr_i32 s23, s22, 31
	v_lshl_add_u64 v[48:49], s[48:49], 0, v[48:49]
	v_lshl_add_u64 v[48:49], s[22:23], 2, v[48:49]
	s_lshl_b32 s44, s83, 2
	v_lshl_add_u64 v[48:49], v[48:49], 0, s[44:45]
	global_store_dword v[48:49], v50, off
.LBB0_7650:
	s_or_b64 exec, exec, s[0:1]
	v_add_u32_e32 v48, 0x90, v140
	s_waitcnt lgkmcnt(0)
	v_ashrrev_i32_e32 v49, 31, v48
	v_lshlrev_b64 v[50:51], 12, v[48:49]
	v_lshl_add_u64 v[50:51], s[38:39], 0, v[50:51]
	v_lshl_add_u64 v[54:55], v[138:139], 1, v[50:51]
	s_waitcnt vmcnt(15)
	v_mov_b64 v[50:51], v[214:215]
	v_mov_b64 v[52:53], v[216:217]
	v_lshlrev_b32_e32 v56, 16, v50
	v_and_b32_e32 v57, 0xffff0000, v50
	v_lshlrev_b32_e32 v50, 16, v51
	v_and_b32_e32 v51, 0xffff0000, v51
	v_lshlrev_b32_e32 v58, 16, v52
	v_and_b32_e32 v59, 0xffff0000, v52
	v_lshlrev_b32_e32 v52, 16, v53
	v_and_b32_e32 v53, 0xffff0000, v53
	v_pk_add_f32 v[50:51], v[46:47], v[50:51]
	v_pk_add_f32 v[56:57], v[44:45], v[56:57]
	v_pk_add_f32 v[52:53], v[42:43], v[52:53]
	v_pk_add_f32 v[58:59], v[40:41], v[58:59]
	v_cvt_pk_bf16_f32 v40, v56, v57
	v_cvt_pk_bf16_f32 v41, v50, v51
	v_mul_f32_e32 v57, v57, v57
	v_cvt_pk_bf16_f32 v42, v58, v59
	v_cvt_pk_bf16_f32 v43, v52, v53
	v_mul_f32_e32 v51, v51, v51
	v_mul_f32_e32 v59, v59, v59
	v_fmac_f32_e32 v57, v56, v56
	v_fmac_f32_e32 v51, v50, v50
	v_mul_f32_e32 v53, v53, v53
	v_fmac_f32_e32 v59, v58, v58
	v_add_f32_e32 v50, v57, v51
	v_fmac_f32_e32 v53, v52, v52
	v_add_f32_e32 v50, v59, v50
	v_add_f32_e32 v56, v53, v50
	global_store_dwordx4 v[54:55], v[40:43], off
	s_waitcnt vmcnt(15)
	v_mov_b64 v[44:45], v[218:219]
	v_mov_b64 v[46:47], v[220:221]
	v_lshlrev_b32_e32 v50, 16, v44
	v_and_b32_e32 v51, 0xffff0000, v44
	v_lshlrev_b32_e32 v44, 16, v45
	v_and_b32_e32 v45, 0xffff0000, v45
	v_lshlrev_b32_e32 v52, 16, v46
	v_and_b32_e32 v53, 0xffff0000, v46
	v_lshlrev_b32_e32 v46, 16, v47
	v_and_b32_e32 v47, 0xffff0000, v47
	v_pk_add_f32 v[38:39], v[38:39], v[44:45]
	v_pk_add_f32 v[36:37], v[36:37], v[50:51]
	v_pk_add_f32 v[44:45], v[34:35], v[46:47]
	v_pk_add_f32 v[46:47], v[32:33], v[52:53]
	v_mul_f32_e32 v32, v37, v37
	v_mul_f32_e32 v33, v39, v39
	v_mul_f32_e32 v34, v47, v47
	v_fmac_f32_e32 v32, v36, v36
	v_fmac_f32_e32 v33, v38, v38
	v_mul_f32_e32 v35, v45, v45
	v_fmac_f32_e32 v34, v46, v46
	v_add_f32_e32 v32, v32, v33
	v_add_f32_e32 v32, v34, v32
	v_fmac_f32_e32 v35, v44, v44
	v_add_f32_e32 v32, v35, v32
	v_add_f32_e32 v32, v56, v32
	ds_bpermute_b32 v33, v114, v32
	v_cvt_pk_bf16_f32 v34, v36, v37
	v_cvt_pk_bf16_f32 v35, v38, v39
	v_cvt_pk_bf16_f32 v36, v46, v47
	v_cvt_pk_bf16_f32 v37, v44, v45
	s_waitcnt lgkmcnt(0)
	v_add_f32_e32 v32, v32, v33
	ds_bpermute_b32 v33, v115, v32
	global_store_dwordx4 v[54:55], v[34:37], off offset:256
	s_and_saveexec_b64 s[0:1], s[34:35]
	s_cbranch_execz .LBB0_7652
	s_waitcnt lgkmcnt(0)
	v_add_f32_e32 v34, v32, v33
	s_lshl_b32 s22, s70, 2
	v_lshlrev_b64 v[32:33], 7, v[48:49]
	s_ashr_i32 s23, s22, 31
	v_lshl_add_u64 v[32:33], s[48:49], 0, v[32:33]
	v_lshl_add_u64 v[32:33], s[22:23], 2, v[32:33]
	s_lshl_b32 s44, s83, 2
	v_lshl_add_u64 v[32:33], v[32:33], 0, s[44:45]
	global_store_dword v[32:33], v34, off
.LBB0_7652:
	s_or_b64 exec, exec, s[0:1]
	v_add_u32_e32 v32, 0xa0, v140
	s_waitcnt lgkmcnt(0)
	v_ashrrev_i32_e32 v33, 31, v32
	v_lshlrev_b64 v[34:35], 12, v[32:33]
	v_lshl_add_u64 v[34:35], s[38:39], 0, v[34:35]
	v_lshl_add_u64 v[38:39], v[138:139], 1, v[34:35]
	s_waitcnt vmcnt(14)
	v_mov_b64 v[34:35], v[168:169]
	v_mov_b64 v[36:37], v[170:171]
	v_lshlrev_b32_e32 v40, 16, v34
	v_and_b32_e32 v41, 0xffff0000, v34
	v_lshlrev_b32_e32 v34, 16, v35
	v_and_b32_e32 v35, 0xffff0000, v35
	v_lshlrev_b32_e32 v42, 16, v36
	v_and_b32_e32 v43, 0xffff0000, v36
	v_lshlrev_b32_e32 v36, 16, v37
	v_and_b32_e32 v37, 0xffff0000, v37
	v_pk_add_f32 v[34:35], v[30:31], v[34:35]
	v_pk_add_f32 v[40:41], v[28:29], v[40:41]
	v_pk_add_f32 v[36:37], v[26:27], v[36:37]
	v_pk_add_f32 v[42:43], v[24:25], v[42:43]
	v_cvt_pk_bf16_f32 v24, v40, v41
	v_cvt_pk_bf16_f32 v25, v34, v35
	v_mul_f32_e32 v41, v41, v41
	v_cvt_pk_bf16_f32 v26, v42, v43
	v_cvt_pk_bf16_f32 v27, v36, v37
	v_mul_f32_e32 v35, v35, v35
	v_mul_f32_e32 v43, v43, v43
	v_fmac_f32_e32 v41, v40, v40
	v_fmac_f32_e32 v35, v34, v34
	v_mul_f32_e32 v37, v37, v37
	v_fmac_f32_e32 v43, v42, v42
	v_add_f32_e32 v34, v41, v35
	v_fmac_f32_e32 v37, v36, v36
	v_add_f32_e32 v34, v43, v34
	v_add_f32_e32 v40, v37, v34
	global_store_dwordx4 v[38:39], v[24:27], off
	s_waitcnt vmcnt(14)
	v_mov_b64 v[28:29], v[172:173]
	v_mov_b64 v[30:31], v[174:175]
	v_lshlrev_b32_e32 v34, 16, v28
	v_and_b32_e32 v35, 0xffff0000, v28
	v_lshlrev_b32_e32 v28, 16, v29
	v_and_b32_e32 v29, 0xffff0000, v29
	v_lshlrev_b32_e32 v36, 16, v30
	v_and_b32_e32 v37, 0xffff0000, v30
	v_lshlrev_b32_e32 v30, 16, v31
	v_and_b32_e32 v31, 0xffff0000, v31
	v_pk_add_f32 v[22:23], v[22:23], v[28:29]
	v_pk_add_f32 v[20:21], v[20:21], v[34:35]
	v_pk_add_f32 v[28:29], v[18:19], v[30:31]
	v_pk_add_f32 v[30:31], v[16:17], v[36:37]
	v_mul_f32_e32 v16, v21, v21
	v_mul_f32_e32 v17, v23, v23
	v_mul_f32_e32 v18, v31, v31
	v_fmac_f32_e32 v16, v20, v20
	v_fmac_f32_e32 v17, v22, v22
	v_mul_f32_e32 v19, v29, v29
	v_fmac_f32_e32 v18, v30, v30
	v_add_f32_e32 v16, v16, v17
	v_add_f32_e32 v16, v18, v16
	v_fmac_f32_e32 v19, v28, v28
	v_add_f32_e32 v16, v19, v16
	v_add_f32_e32 v16, v40, v16
	ds_bpermute_b32 v17, v114, v16
	v_cvt_pk_bf16_f32 v18, v20, v21
	v_cvt_pk_bf16_f32 v19, v22, v23
	v_cvt_pk_bf16_f32 v20, v30, v31
	v_cvt_pk_bf16_f32 v21, v28, v29
	s_waitcnt lgkmcnt(0)
	v_add_f32_e32 v16, v16, v17
	ds_bpermute_b32 v17, v115, v16
	global_store_dwordx4 v[38:39], v[18:21], off offset:256
	s_and_saveexec_b64 s[0:1], s[34:35]
	s_cbranch_execz .LBB0_7654
	s_waitcnt lgkmcnt(0)
	v_add_f32_e32 v18, v16, v17
	s_lshl_b32 s22, s70, 2
	v_lshlrev_b64 v[16:17], 7, v[32:33]
	s_ashr_i32 s23, s22, 31
	v_lshl_add_u64 v[16:17], s[48:49], 0, v[16:17]
	v_lshl_add_u64 v[16:17], s[22:23], 2, v[16:17]
	s_lshl_b32 s44, s83, 2
	v_lshl_add_u64 v[16:17], v[16:17], 0, s[44:45]
	global_store_dword v[16:17], v18, off
.LBB0_7654:
	s_or_b64 exec, exec, s[0:1]
	v_add_u32_e32 v16, 0xb0, v140
	s_waitcnt lgkmcnt(0)
	v_ashrrev_i32_e32 v17, 31, v16
	v_lshlrev_b64 v[18:19], 12, v[16:17]
	v_lshl_add_u64 v[18:19], s[38:39], 0, v[18:19]
	v_lshl_add_u64 v[22:23], v[138:139], 1, v[18:19]
	s_waitcnt vmcnt(12)
	v_mov_b64 v[18:19], v[176:177]
	v_mov_b64 v[20:21], v[178:179]
	v_lshlrev_b32_e32 v24, 16, v18
	v_and_b32_e32 v25, 0xffff0000, v18
	v_lshlrev_b32_e32 v18, 16, v19
	v_and_b32_e32 v19, 0xffff0000, v19
	v_lshlrev_b32_e32 v26, 16, v20
	v_and_b32_e32 v27, 0xffff0000, v20
	v_lshlrev_b32_e32 v20, 16, v21
	v_and_b32_e32 v21, 0xffff0000, v21
	v_pk_add_f32 v[18:19], v[14:15], v[18:19]
	v_pk_add_f32 v[24:25], v[12:13], v[24:25]
	v_pk_add_f32 v[20:21], v[10:11], v[20:21]
	v_pk_add_f32 v[26:27], v[8:9], v[26:27]
	v_cvt_pk_bf16_f32 v8, v24, v25
	v_cvt_pk_bf16_f32 v9, v18, v19
	v_mul_f32_e32 v25, v25, v25
	v_cvt_pk_bf16_f32 v10, v26, v27
	v_cvt_pk_bf16_f32 v11, v20, v21
	v_mul_f32_e32 v19, v19, v19
	v_mul_f32_e32 v27, v27, v27
	v_fmac_f32_e32 v25, v24, v24
	v_fmac_f32_e32 v19, v18, v18
	v_mul_f32_e32 v21, v21, v21
	v_fmac_f32_e32 v27, v26, v26
	v_add_f32_e32 v18, v25, v19
	v_fmac_f32_e32 v21, v20, v20
	v_add_f32_e32 v18, v27, v18
	v_add_f32_e32 v24, v21, v18
	global_store_dwordx4 v[22:23], v[8:11], off
	s_waitcnt vmcnt(12)
	v_mov_b64 v[12:13], v[180:181]
	v_mov_b64 v[14:15], v[182:183]
	v_lshlrev_b32_e32 v18, 16, v12
	v_and_b32_e32 v19, 0xffff0000, v12
	v_lshlrev_b32_e32 v12, 16, v13
	v_and_b32_e32 v13, 0xffff0000, v13
	v_lshlrev_b32_e32 v20, 16, v14
	v_and_b32_e32 v21, 0xffff0000, v14
	v_lshlrev_b32_e32 v14, 16, v15
	v_and_b32_e32 v15, 0xffff0000, v15
	v_pk_add_f32 v[6:7], v[6:7], v[12:13]
	v_pk_add_f32 v[4:5], v[4:5], v[18:19]
	v_pk_add_f32 v[12:13], v[2:3], v[14:15]
	v_pk_add_f32 v[14:15], v[0:1], v[20:21]
	v_mul_f32_e32 v0, v5, v5
	v_mul_f32_e32 v1, v7, v7
	v_mul_f32_e32 v2, v15, v15
	v_fmac_f32_e32 v0, v4, v4
	v_fmac_f32_e32 v1, v6, v6
	v_mul_f32_e32 v3, v13, v13
	v_fmac_f32_e32 v2, v14, v14
	v_add_f32_e32 v0, v0, v1
	v_add_f32_e32 v0, v2, v0
	v_fmac_f32_e32 v3, v12, v12
	v_add_f32_e32 v0, v3, v0
	v_add_f32_e32 v0, v24, v0
	ds_bpermute_b32 v1, v114, v0
	v_cvt_pk_bf16_f32 v2, v4, v5
	v_cvt_pk_bf16_f32 v3, v6, v7
	v_cvt_pk_bf16_f32 v4, v14, v15
	v_cvt_pk_bf16_f32 v5, v12, v13
	s_waitcnt lgkmcnt(0)
	v_add_f32_e32 v0, v0, v1
	ds_bpermute_b32 v1, v115, v0
	global_store_dwordx4 v[22:23], v[2:5], off offset:256
	s_and_saveexec_b64 s[0:1], s[34:35]
	s_cbranch_execz .LBB0_7656
	s_waitcnt lgkmcnt(0)
	v_add_f32_e32 v2, v0, v1
	s_lshl_b32 s22, s70, 2
	v_lshlrev_b64 v[0:1], 7, v[16:17]
	s_ashr_i32 s23, s22, 31
	v_lshl_add_u64 v[0:1], s[48:49], 0, v[0:1]
	v_lshl_add_u64 v[0:1], s[22:23], 2, v[0:1]
	s_lshl_b32 s44, s83, 2
	v_lshl_add_u64 v[0:1], v[0:1], 0, s[44:45]
	global_store_dword v[0:1], v2, off
